# v33 + GEMM phase prologue: all 14 staging loads of K-tiles 0/1 issued before the first wait+barrier (vmcnt(8))
# speedup vs baseline: 1.0013x; 1.0002x over previous
.LBB0_134:
	v_lshrrev_b32_e32 v16, 1, v6
	v_and_b32_e32 v16, 24, v16
	v_and_b32_e32 v7, 15, v6
	v_lshlrev_b32_e32 v17, 1, v16
	v_lshlrev_b32_e32 v6, 2, v6
	s_lshl_b32 s17, s17, 5
	v_mov_b32_e32 v133, v161
	v_lshl_or_b32 v141, s24, 6, v7
	v_lshl_or_b32 v7, v7, 6, v17
	s_lshl_b32 s24, s24, 13
	v_and_b32_e32 v6, 32, v6
	s_and_b32 s46, s17, 0x60
	v_lshl_add_u64 v[8:9], s[4:5], 0, v[132:133]
	v_mov_b32_e32 v129, v161
	v_readlane_b32 s38, v255, 23
	v_bitop3_b32 v17, v7, s24, v6 bitop3:0xde
	s_lshl_b32 s24, s46, 7
	v_lshl_add_u64 v[10:11], s[4:5], 0, v[128:129]
	v_mov_b32_e32 v135, v161
	v_readlane_b32 s39, v255, 24
	v_bitop3_b32 v144, v7, s24, v6 bitop3:0xde
	s_add_i32 m0, s42, 0x18000
	v_lshl_add_u64 v[6:7], v[8:9], 0, s[14:15]
	v_lshl_add_u64 v[12:13], s[38:39], 0, v[134:135]
	v_mov_b32_e32 v131, v161
	global_load_lds_dwordx4 v[6:7], off
	v_lshl_add_u64 v[6:7], v[10:11], 0, s[14:15]
	s_add_i32 m0, s42, 0x1a000
	s_add_i32 s47, s42, 0x8000
	s_add_i32 s48, s42, 0xa000
	v_lshl_add_u64 v[14:15], s[38:39], 0, v[130:131]
	global_load_lds_dwordx4 v[6:7], off
	v_lshl_add_u64 v[6:7], v[12:13], 0, s[14:15]
	s_mov_b32 m0, s47
	s_add_u32 s24, s4, 0x80080
	global_load_lds_dwordx4 v[6:7], off
	v_lshl_add_u64 v[6:7], v[14:15], 0, s[14:15]
	s_mov_b32 m0, s48
	s_addc_u32 s25, s5, 0
	global_load_lds_dwordx4 v[6:7], off
	s_add_i32 m0, s42, 0x1c000
	v_lshl_add_u64 v[6:7], s[24:25], 0, v[132:133]
	global_load_lds_dwordx4 v[6:7], off
	v_lshl_add_u64 v[6:7], s[24:25], 0, v[128:129]
	s_add_i32 m0, s42, 0x1e000
	s_cmpk_lt_u32 s16, 0x100
	global_load_lds_dwordx4 v[6:7], off
	s_waitcnt vmcnt(8)
	s_barrier
	v_lshlrev_b32_e32 v7, 15, v4
	v_and_b32_e32 v7, 0xffff0000, v7
	v_lshl_add_u32 v3, v3, 12, v7
	v_and_b32_e32 v4, 1, v4
	v_lshl_or_b32 v3, v4, 6, v3
	v_lshl_add_u32 v136, v5, 1, v3
	v_lshlrev_b32_e32 v3, 15, v0
	v_and_b32_e32 v3, 0xffff0000, v3
	s_waitcnt vmcnt(6)
	v_lshl_add_u32 v1, v1, 12, v3
	v_and_b32_e32 v0, 1, v0
	v_and_or_b32 v6, s17, 32, v16
	v_lshl_or_b32 v0, v0, 6, v1
	v_readlane_b32 s26, v255, 19
	s_cselect_b64 s[24:25], -1, 0
	v_mov_b32_e32 v137, v161
	v_lshl_add_u32 v138, v2, 1, v0
	v_mov_b32_e32 v139, v161
	s_mov_b32 s49, 0
	v_add_u32_e32 v145, 0, v17
	v_lshlrev_b32_e32 v160, 1, v6
	v_readlane_b32 s16, v255, 18
	s_mov_b32 s17, s26
	s_barrier
	v_readlane_b32 s27, v255, 20
	s_branch .LBB0_137

.LBB0_176:
	v_mov_b32_e32 v131, v161
	v_lshl_add_u64 v[8:9], s[4:5], 0, v[130:131]
	v_mov_b32_e32 v135, v161
	s_lshl_b32 s27, s24, 5
	v_lshl_add_u64 v[10:11], s[4:5], 0, v[134:135]
	v_mov_b32_e32 v129, v161
	s_and_b32 s54, s27, 0x60
	s_add_i32 m0, s43, 0x18000
	v_lshl_add_u64 v[8:9], v[8:9], 0, s[14:15]
	v_lshl_add_u64 v[12:13], s[46:47], 0, v[128:129]
	v_mov_b32_e32 v133, v161
	s_lshl_b32 s26, s16, 13
	s_lshl_b32 s28, s54, 7
	global_load_lds_dwordx4 v[8:9], off
	v_lshl_add_u64 v[8:9], v[10:11], 0, s[14:15]
	s_add_i32 m0, s43, 0x1a000
	s_add_i32 s55, s43, 0x8000
	s_add_i32 s56, s43, 0xa000
	v_lshl_add_u64 v[14:15], s[46:47], 0, v[132:133]
	global_load_lds_dwordx4 v[8:9], off
	v_lshl_add_u64 v[8:9], v[12:13], 0, s[14:15]
	s_mov_b32 m0, s55
	s_add_u32 s24, s4, 0x80080
	global_load_lds_dwordx4 v[8:9], off
	v_lshl_add_u64 v[8:9], v[14:15], 0, s[14:15]
	s_mov_b32 m0, s56
	s_addc_u32 s25, s5, 0
	global_load_lds_dwordx4 v[8:9], off
	s_add_i32 m0, s43, 0x1c000
	v_lshl_add_u64 v[8:9], s[24:25], 0, v[130:131]
	global_load_lds_dwordx4 v[8:9], off
	v_lshl_add_u64 v[8:9], s[24:25], 0, v[134:135]
	s_add_i32 m0, s43, 0x1e000
	v_and_b32_e32 v7, 15, v0
	global_load_lds_dwordx4 v[8:9], off
	s_waitcnt vmcnt(8)
	s_barrier
	v_lshrrev_b32_e32 v8, 1, v0
	v_and_b32_e32 v8, 24, v8
	v_lshlrev_b32_e32 v9, 1, v8
	v_lshlrev_b32_e32 v0, 2, v0
	v_lshl_or_b32 v148, s16, 6, v7
	v_lshl_or_b32 v7, v7, 6, v9
	v_and_b32_e32 v0, 32, v0
	v_bitop3_b32 v9, v7, s26, v0 bitop3:0xde
	v_bitop3_b32 v149, v7, s28, v0 bitop3:0xde
	v_lshlrev_b32_e32 v7, 15, v1
	v_and_b32_e32 v7, 0xffff0000, v7
	v_lshl_add_u32 v2, v2, 12, v7
	v_and_b32_e32 v1, 1, v1
	v_lshl_or_b32 v1, v1, 6, v2
	v_lshl_add_u32 v136, v3, 1, v1
	v_lshlrev_b32_e32 v1, 15, v4
	v_and_b32_e32 v1, 0xffff0000, v1
	s_waitcnt vmcnt(6)
	v_or_b32_e32 v0, s54, v8
	v_lshl_add_u32 v1, v5, 12, v1
	v_and_b32_e32 v2, 1, v4
	v_or_b32_e32 v150, 0xfffff800, v0
	s_cmpk_lt_u32 s17, 0x100
	v_and_or_b32 v0, s27, 32, v8
	v_lshl_or_b32 v1, v2, 6, v1
	s_mov_b32 s16, 32
	s_cselect_b64 s[24:25], -1, 0
	v_mov_b32_e32 v137, v161
	v_lshl_add_u32 v138, v6, 1, v1
	v_mov_b32_e32 v139, v161
	s_mov_b32 s63, 0
	v_add_u32_e32 v151, 0, v9
	v_lshlrev_b32_e32 v140, 1, v0
	s_mov_b32 s17, 0
	s_barrier
	s_branch .LBB0_179

.LBB0_549:
	v_lshl_add_u64 v[6:7], s[4:5], 0, v[160:161]
	v_mov_b32_e32 v129, v161
	v_readlane_b32 s20, v255, 34
	v_and_b32_e32 v236, 15, v142
	v_and_b32_e32 v14, 48, v142
	v_lshlrev_b32_e32 v15, 2, v142
	v_lshl_add_u64 v[8:9], s[4:5], 0, v[128:129]
	v_mov_b32_e32 v133, v161
	v_readlane_b32 s21, v255, 35
	s_and_b32 s42, s13, 3
	s_lshl_b32 s12, s18, 13
	v_lshl_or_b32 v14, v236, 6, v14
	v_and_b32_e32 v15, 32, v15
	s_add_i32 m0, s45, 0x18000
	v_lshl_add_u64 v[6:7], v[6:7], 0, s[14:15]
	v_lshl_add_u64 v[10:11], s[20:21], 0, v[132:133]
	v_mov_b32_e32 v131, v161
	v_bitop3_b32 v16, v14, s12, v15 bitop3:0xde
	s_lshl_b32 s12, s42, 12
	global_load_lds_dwordx4 v[6:7], off
	v_lshl_add_u64 v[6:7], v[8:9], 0, s[14:15]
	s_add_i32 m0, s45, 0x1a000
	s_add_i32 s49, s45, 0x8000
	s_add_i32 s52, s45, 0xa000
	v_lshl_add_u64 v[12:13], s[20:21], 0, v[130:131]
	global_load_lds_dwordx4 v[6:7], off
	v_lshl_add_u64 v[6:7], v[10:11], 0, s[14:15]
	s_mov_b32 m0, s49
	s_add_u32 s16, s4, 0x80080
	global_load_lds_dwordx4 v[6:7], off
	v_lshl_add_u64 v[6:7], v[12:13], 0, s[14:15]
	s_mov_b32 m0, s52
	s_addc_u32 s17, s5, 0
	global_load_lds_dwordx4 v[6:7], off
	s_add_i32 m0, s45, 0x1c000
	v_lshl_add_u64 v[6:7], s[16:17], 0, v[160:161]
	global_load_lds_dwordx4 v[6:7], off
	v_lshl_add_u64 v[6:7], s[16:17], 0, v[128:129]
	s_add_i32 m0, s45, 0x1e000
	v_readlane_b32 s16, v255, 32
	global_load_lds_dwordx4 v[6:7], off
	s_waitcnt vmcnt(8)
	s_barrier
	v_lshlrev_b32_e32 v6, 15, v4
	v_and_b32_e32 v6, 0xffff0000, v6
	v_lshl_add_u32 v3, v3, 12, v6
	v_and_b32_e32 v4, 1, v4
	v_lshl_or_b32 v3, v4, 6, v3
	v_lshl_add_u32 v134, v5, 1, v3
	v_lshlrev_b32_e32 v3, 15, v0
	v_and_b32_e32 v3, 0xffff0000, v3
	v_lshl_add_u32 v1, v1, 12, v3
	v_and_b32_e32 v0, 1, v0
	s_waitcnt vmcnt(6)
	v_lshl_or_b32 v0, v0, 6, v1
	v_lshl_add_u32 v136, v2, 1, v0
	v_mov_b32_e32 v0, 0
	v_lshl_or_b32 v188, s18, 6, v236
	v_bitop3_b32 v143, v14, s12, v15 bitop3:0xde
	v_mov_b32_e32 v135, v161
	v_mov_b32_e32 v137, v161
	s_mov_b32 s53, 0
	v_add_u32_e32 v144, 0, v16
	v_readlane_b32 s12, v255, 29
	s_mov_b32 s19, s16
	v_mov_b32_e32 v1, v0
	v_mov_b32_e32 v2, v0
	v_mov_b32_e32 v3, v0
	v_mov_b32_e32 v4, v0
	v_mov_b32_e32 v5, v0
	v_mov_b32_e32 v6, v0
	v_mov_b32_e32 v7, v0
	v_mov_b32_e32 v16, v0
	v_mov_b32_e32 v17, v0
	v_mov_b32_e32 v18, v0
	v_mov_b32_e32 v19, v0
	v_mov_b32_e32 v20, v0
	v_mov_b32_e32 v21, v0
	v_mov_b32_e32 v22, v0
	v_mov_b32_e32 v23, v0
	v_mov_b32_e32 v32, v0
	v_mov_b32_e32 v33, v0
	v_mov_b32_e32 v34, v0
	v_mov_b32_e32 v35, v0
	v_mov_b32_e32 v36, v0
	v_mov_b32_e32 v37, v0
	v_mov_b32_e32 v38, v0
	v_mov_b32_e32 v39, v0
	v_mov_b32_e32 v48, v0
	v_mov_b32_e32 v49, v0
	v_mov_b32_e32 v50, v0
	v_mov_b32_e32 v51, v0
	v_mov_b32_e32 v52, v0
	v_mov_b32_e32 v53, v0
	v_mov_b32_e32 v54, v0
	v_mov_b32_e32 v55, v0
	v_mov_b32_e32 v8, v0
	v_mov_b32_e32 v9, v0
	v_mov_b32_e32 v10, v0
	v_mov_b32_e32 v11, v0
	v_mov_b32_e32 v12, v0
	v_mov_b32_e32 v13, v0
	v_mov_b32_e32 v14, v0
	v_mov_b32_e32 v15, v0
	v_mov_b32_e32 v24, v0
	v_mov_b32_e32 v25, v0
	v_mov_b32_e32 v26, v0
	v_mov_b32_e32 v27, v0
	v_mov_b32_e32 v28, v0
	v_mov_b32_e32 v29, v0
	v_mov_b32_e32 v30, v0
	v_mov_b32_e32 v31, v0
	v_mov_b32_e32 v40, v0
	v_mov_b32_e32 v41, v0
	v_mov_b32_e32 v42, v0
	v_mov_b32_e32 v43, v0
	v_mov_b32_e32 v44, v0
	v_mov_b32_e32 v45, v0
	v_mov_b32_e32 v46, v0
	v_mov_b32_e32 v47, v0
	v_mov_b32_e32 v56, v0
	v_mov_b32_e32 v57, v0
	v_mov_b32_e32 v58, v0
	v_mov_b32_e32 v59, v0
	v_mov_b32_e32 v60, v0
	v_mov_b32_e32 v61, v0
	v_mov_b32_e32 v62, v0
	v_mov_b32_e32 v63, v0
	v_mov_b32_e32 v64, v0
	v_mov_b32_e32 v65, v0
	v_mov_b32_e32 v66, v0
	v_mov_b32_e32 v67, v0
	v_mov_b32_e32 v68, v0
	v_mov_b32_e32 v69, v0
	v_mov_b32_e32 v70, v0
	v_mov_b32_e32 v71, v0
	v_mov_b32_e32 v80, v0
	v_mov_b32_e32 v81, v0
	v_mov_b32_e32 v82, v0
	v_mov_b32_e32 v83, v0
	v_mov_b32_e32 v84, v0
	v_mov_b32_e32 v85, v0
	v_mov_b32_e32 v86, v0
	v_mov_b32_e32 v87, v0
	v_mov_b32_e32 v96, v0
	v_mov_b32_e32 v97, v0
	v_mov_b32_e32 v98, v0
	v_mov_b32_e32 v99, v0
	v_mov_b32_e32 v100, v0
	v_mov_b32_e32 v101, v0
	v_mov_b32_e32 v102, v0
	v_mov_b32_e32 v103, v0
	v_mov_b32_e32 v116, v0
	v_mov_b32_e32 v117, v0
	v_mov_b32_e32 v118, v0
	v_mov_b32_e32 v119, v0
	v_mov_b32_e32 v108, v0
	v_mov_b32_e32 v109, v0
	v_mov_b32_e32 v110, v0
	v_mov_b32_e32 v111, v0
	v_mov_b32_e32 v72, v0
	v_mov_b32_e32 v73, v0
	v_mov_b32_e32 v74, v0
	v_mov_b32_e32 v75, v0
	v_mov_b32_e32 v76, v0
	v_mov_b32_e32 v77, v0
	v_mov_b32_e32 v78, v0
	v_mov_b32_e32 v79, v0
	v_mov_b32_e32 v88, v0
	v_mov_b32_e32 v89, v0
	v_mov_b32_e32 v90, v0
	v_mov_b32_e32 v91, v0
	v_mov_b32_e32 v92, v0
	v_mov_b32_e32 v93, v0
	v_mov_b32_e32 v94, v0
	v_mov_b32_e32 v95, v0
	v_mov_b32_e32 v104, v0
	v_mov_b32_e32 v105, v0
	v_mov_b32_e32 v106, v0
	v_mov_b32_e32 v107, v0
	v_mov_b32_e32 v112, v0
	v_mov_b32_e32 v113, v0
	v_mov_b32_e32 v114, v0
	v_mov_b32_e32 v115, v0
	v_mov_b32_e32 v124, v0
	v_mov_b32_e32 v125, v0
	v_mov_b32_e32 v126, v0
	v_mov_b32_e32 v127, v0
	v_mov_b32_e32 v120, v0
	v_mov_b32_e32 v121, v0
	v_mov_b32_e32 v122, v0
	v_mov_b32_e32 v123, v0
	s_barrier
	v_readlane_b32 s17, v255, 33
